# phase 0: sc1 nt (instead of nt) on most weight-transpose loads
# speedup vs baseline: 1.0053x; 1.0053x over previous
.LBB0_24:
	s_cmpk_gt_i32 s90, 0x11ff
	s_mov_b64 s[16:17], -1
	s_cbranch_scc0 .LBB0_59
	s_cmpk_gt_u32 s90, 0x13ff
	s_cbranch_scc0 .LBB0_56
	s_cmpk_gt_u32 s90, 0x17ff
	s_cbranch_scc0 .LBB0_50
	s_cmpk_gt_u32 s90, 0x19ff
	s_cbranch_scc0 .LBB0_44
	s_cmpk_gt_u32 s90, 0x1bff
	s_cbranch_scc0 .LBB0_41
	s_cmpk_gt_u32 s90, 0x31ff
	s_cbranch_scc0 .LBB0_31
	s_add_i32 s6, s90, 0xffffce00
	s_add_i32 s16, s90, 0xffffc880
	s_cmpk_lt_u32 s6, 0x580
	s_cselect_b32 s16, s6, s16
	s_cmpk_gt_u32 s6, 0x57f
	s_cselect_b32 s6, 0xb00000, 0
	s_cselect_b32 s26, 0x580000, 0
	s_add_u32 s72, s24, s6
	s_addc_u32 s73, s25, 0
	s_lshl_b32 s6, s16, 1
	s_and_b32 s17, s6, 0xfc0
	s_lshl_b32 s6, s16, 5
	s_and_b32 s16, s6, 0x3e0
	v_or_b32_e32 v0, s17, v30
	s_add_u32 s26, s34, s26
	v_lshlrev_b32_e32 v0, 12, v0
	v_mov_b32_e32 v1, v9
	s_addc_u32 s27, s35, 0
	v_lshl_add_u64 v[0:1], s[72:73], 0, v[0:1]
	s_lshl_b32 s6, s16, 2
	v_lshl_add_u64 v[0:1], v[0:1], 0, s[6:7]
	v_lshl_add_u64 v[0:1], v[0:1], 0, v[8:9]
	s_movk_i32 s6, 0x2000
	v_add_co_u32_e32 v2, vcc, s6, v0
	s_movk_i32 s6, 0x4000
	s_nop 0
	v_addc_co_u32_e32 v3, vcc, 0, v1, vcc
	v_add_co_u32_e32 v4, vcc, s6, v0
	s_movk_i32 s6, 0x6000
	s_nop 0
	v_addc_co_u32_e32 v5, vcc, 0, v1, vcc
	v_add_co_u32_e32 v6, vcc, s6, v0
	s_mov_b32 s6, 0x8000
	s_nop 0
	v_addc_co_u32_e32 v7, vcc, 0, v1, vcc
	v_add_co_u32_e32 v44, vcc, s6, v0
	s_mov_b32 s6, 0xa000
	s_nop 0
	v_addc_co_u32_e32 v45, vcc, 0, v1, vcc
	v_add_co_u32_e32 v46, vcc, s6, v0
	s_mov_b32 s6, 0xc000
	s_nop 0
	v_addc_co_u32_e32 v47, vcc, 0, v1, vcc
	v_add_co_u32_e32 v48, vcc, s6, v0
	s_mov_b32 s6, 0xe000
	s_nop 0
	v_addc_co_u32_e32 v49, vcc, 0, v1, vcc
	v_add_co_u32_e32 v50, vcc, s6, v0
	s_mov_b32 s6, 0x10000
	s_nop 0
	v_addc_co_u32_e32 v51, vcc, 0, v1, vcc
	global_load_dword v27, v[0:1], off sc1 nt
	global_load_dword v54, v[2:3], off sc1 nt
	global_load_dword v55, v[4:5], off sc1 nt
	global_load_dword v56, v[6:7], off sc1 nt
	global_load_dword v57, v[44:45], off sc1 nt
	global_load_dword v58, v[46:47], off sc1 nt
	global_load_dword v59, v[48:49], off sc1 nt
	global_load_dword v60, v[50:51], off sc1 nt
	v_add_co_u32_e32 v2, vcc, s6, v0
	s_mov_b32 s6, 0x14000
	s_nop 0
	v_addc_co_u32_e32 v3, vcc, 0, v1, vcc
	v_add_co_u32_e32 v4, vcc, s42, v0
	v_readlane_b32 s72, v254, 10
	s_nop 0
	v_addc_co_u32_e32 v5, vcc, 0, v1, vcc
	v_add_co_u32_e32 v6, vcc, s6, v0
	s_mov_b32 s6, 0x18000
	s_nop 0
	v_addc_co_u32_e32 v7, vcc, 0, v1, vcc
	v_add_co_u32_e32 v44, vcc, s43, v0
	s_nop 1
	v_addc_co_u32_e32 v45, vcc, 0, v1, vcc
	v_add_co_u32_e32 v46, vcc, s6, v0
	s_mov_b32 s6, 0x1a000
	s_nop 0
	v_addc_co_u32_e32 v47, vcc, 0, v1, vcc
	v_add_co_u32_e32 v48, vcc, s6, v0
	s_mov_b32 s6, 0x1c000
	s_nop 0
	v_addc_co_u32_e32 v49, vcc, 0, v1, vcc
	v_add_co_u32_e32 v50, vcc, s6, v0
	s_mov_b32 s6, 0x1e000
	s_nop 0
	v_addc_co_u32_e32 v51, vcc, 0, v1, vcc
	v_add_co_u32_e32 v52, vcc, s6, v0
	s_mov_b32 s6, 0x20000
	s_nop 0
	v_addc_co_u32_e32 v53, vcc, 0, v1, vcc
	global_load_dword v61, v[2:3], off sc1 nt
	global_load_dword v62, v[4:5], off sc1 nt
	global_load_dword v63, v[6:7], off sc1 nt
	global_load_dword v64, v[44:45], off sc1 nt
	global_load_dword v65, v[46:47], off sc1 nt
	global_load_dword v66, v[48:49], off sc1 nt
	global_load_dword v67, v[50:51], off sc1 nt
	global_load_dword v68, v[52:53], off sc1 nt
	v_add_co_u32_e32 v2, vcc, s6, v0
	s_mov_b32 s6, 0x22000
	s_nop 0
	v_addc_co_u32_e32 v3, vcc, 0, v1, vcc
	v_add_co_u32_e32 v4, vcc, s6, v0
	s_mov_b32 s6, 0x26000
	s_nop 0
	v_addc_co_u32_e32 v5, vcc, 0, v1, vcc
	v_add_co_u32_e32 v6, vcc, s44, v0
	s_nop 1
	v_addc_co_u32_e32 v7, vcc, 0, v1, vcc
	v_add_co_u32_e32 v44, vcc, s6, v0
	s_mov_b32 s6, 0x28000
	s_nop 0
	v_addc_co_u32_e32 v45, vcc, 0, v1, vcc
	v_add_co_u32_e32 v46, vcc, s6, v0
	s_mov_b32 s6, 0x2a000
	s_nop 0
	v_addc_co_u32_e32 v47, vcc, 0, v1, vcc
	v_add_co_u32_e32 v48, vcc, s6, v0
	s_mov_b32 s6, 0x2e000
	s_nop 0
	v_addc_co_u32_e32 v49, vcc, 0, v1, vcc
	v_add_co_u32_e32 v50, vcc, s45, v0
	s_nop 1
	v_addc_co_u32_e32 v51, vcc, 0, v1, vcc
	v_add_co_u32_e32 v52, vcc, s6, v0
	s_mov_b32 s6, 0x30000
	s_nop 0
	v_addc_co_u32_e32 v53, vcc, 0, v1, vcc
	global_load_dword v69, v[2:3], off sc1 nt
	global_load_dword v70, v[4:5], off sc1 nt
	global_load_dword v71, v[6:7], off sc1 nt
	global_load_dword v72, v[44:45], off sc1 nt
	global_load_dword v73, v[46:47], off sc1 nt
	global_load_dword v74, v[48:49], off sc1 nt
	global_load_dword v75, v[50:51], off sc1 nt
	s_nop 0
	global_load_dword v52, v[52:53], off sc1 nt
	v_add_co_u32_e32 v2, vcc, s6, v0
	s_mov_b32 s6, 0x32000
	s_nop 0
	v_addc_co_u32_e32 v3, vcc, 0, v1, vcc
	v_add_co_u32_e32 v4, vcc, s6, v0
	s_mov_b32 s6, 0x34000
	s_nop 0
	v_addc_co_u32_e32 v5, vcc, 0, v1, vcc
	v_add_co_u32_e32 v6, vcc, s6, v0
	s_mov_b32 s6, 0x38000
	s_nop 0
	v_addc_co_u32_e32 v7, vcc, 0, v1, vcc
	v_add_co_u32_e32 v44, vcc, s46, v0
	s_nop 1
	v_addc_co_u32_e32 v45, vcc, 0, v1, vcc
	v_add_co_u32_e32 v46, vcc, s6, v0
	s_mov_b32 s6, 0x3a000
	s_nop 0
	v_addc_co_u32_e32 v47, vcc, 0, v1, vcc
	v_add_co_u32_e32 v48, vcc, s6, v0
	s_mov_b32 s6, 0x3c000
	s_nop 0
	v_addc_co_u32_e32 v49, vcc, 0, v1, vcc
	v_add_co_u32_e32 v50, vcc, s6, v0
	s_mov_b32 s6, 0x3e000
	s_nop 0
	v_addc_co_u32_e32 v51, vcc, 0, v1, vcc
	v_add_co_u32_e32 v0, vcc, s6, v0
	s_lshl_b32 s6, s17, 1
	s_nop 0
	v_addc_co_u32_e32 v1, vcc, 0, v1, vcc
	global_load_dword v2, v[2:3], off sc1 nt
	s_nop 0
	global_load_dword v3, v[4:5], off sc1 nt
	s_nop 0
	global_load_dword v4, v[6:7], off sc1 nt
	global_load_dword v5, v[44:45], off sc1 nt
	s_nop 0
	global_load_dword v6, v[46:47], off sc1 nt
	global_load_dword v7, v[48:49], off sc1 nt
	global_load_dword v44, v[50:51], off sc1 nt
	s_nop 0
	global_load_dword v0, v[0:1], off sc1 nt
	s_waitcnt vmcnt(16)
	s_waitcnt vmcnt(0)
	ds_write2_b32 v31, v27, v54 offset1:66
	ds_write2_b32 v31, v55, v56 offset0:132 offset1:198
	ds_write2_b32 v37, v57, v58 offset0:8 offset1:74
	ds_write2_b32 v37, v59, v60 offset0:140 offset1:206
	ds_write2_b32 v38, v61, v62 offset0:16 offset1:82
	ds_write2_b32 v38, v63, v64 offset0:148 offset1:214
	ds_write2_b32 v39, v65, v66 offset0:24 offset1:90
	ds_write2_b32 v39, v67, v68 offset0:156 offset1:222
	ds_write2_b32 v40, v69, v70 offset0:32 offset1:98
	ds_write2_b32 v40, v71, v72 offset0:164 offset1:230
	ds_write2_b32 v41, v73, v74 offset0:40 offset1:106
	ds_write2_b32 v41, v75, v52 offset0:172 offset1:238
	ds_write2_b32 v42, v2, v3 offset0:48 offset1:114
	ds_write2_b32 v42, v4, v5 offset0:180 offset1:246
	ds_write2_b32 v43, v6, v7 offset0:56 offset1:122
	ds_write2_b32 v43, v44, v0 offset0:188 offset1:254
	s_waitcnt lgkmcnt(0)
	ds_read2_b32 v[4:5], v33 offset0:33 offset1:41
	ds_read2_b32 v[6:7], v33 offset1:8
	ds_read2_b32 v[44:45], v33 offset0:66 offset1:74
	ds_read2_b32 v[46:47], v33 offset0:99 offset1:107
	ds_read2_b32 v[48:49], v33 offset0:132 offset1:140
	ds_read2_b32 v[50:51], v33 offset0:165 offset1:173
	ds_read2_b32 v[52:53], v33 offset0:198 offset1:206
	ds_read2_b32 v[54:55], v33 offset0:231 offset1:239
	s_add_u32 s26, s26, s6
	s_waitcnt lgkmcnt(6)
	v_cvt_pk_bf16_f32 v0, v6, v4
	v_or_b32_e32 v4, s16, v32
	s_addc_u32 s27, s27, 0
	v_mov_b32_e32 v27, v9
	v_mul_u32_u24_e32 v4, 0xb00, v4
	v_lshl_add_u64 v[56:57], s[26:27], 0, v[26:27]
	v_lshlrev_b32_e32 v58, 1, v4
	v_mov_b32_e32 v59, v9
	s_waitcnt lgkmcnt(4)
	v_cvt_pk_bf16_f32 v1, v44, v46
	s_waitcnt lgkmcnt(2)
	v_cvt_pk_bf16_f32 v2, v48, v50
	s_waitcnt lgkmcnt(0)
	v_cvt_pk_bf16_f32 v3, v52, v54
	v_lshl_add_u64 v[58:59], v[56:57], 0, v[58:59]
	v_or_b32_e32 v4, s16, v34
	global_store_dwordx4 v[58:59], v[0:3], off
	v_mul_u32_u24_e32 v4, 0xb00, v4
	v_lshlrev_b32_e32 v4, 1, v4
	v_cvt_pk_bf16_f32 v0, v7, v5
	v_cvt_pk_bf16_f32 v1, v45, v47
	v_cvt_pk_bf16_f32 v2, v49, v51
	v_cvt_pk_bf16_f32 v3, v53, v55
	v_mov_b32_e32 v5, v9
	ds_read2_b32 v[6:7], v33 offset0:16 offset1:24
	ds_read2_b32 v[44:45], v33 offset0:49 offset1:57
	ds_read2_b32 v[46:47], v33 offset0:82 offset1:90
	ds_read2_b32 v[48:49], v33 offset0:115 offset1:123
	ds_read2_b32 v[50:51], v33 offset0:148 offset1:156
	ds_read2_b32 v[52:53], v33 offset0:181 offset1:189
	ds_read2_b32 v[54:55], v33 offset0:214 offset1:222
	ds_read2_b32 v[58:59], v33 offset0:247 offset1:255
	v_lshl_add_u64 v[4:5], v[56:57], 0, v[4:5]
	global_store_dwordx4 v[4:5], v[0:3], off
	v_or_b32_e32 v4, s16, v35
	v_mul_u32_u24_e32 v4, 0xb00, v4
	v_lshlrev_b32_e32 v4, 1, v4
	v_mov_b32_e32 v5, v9
	s_waitcnt lgkmcnt(6)
	v_cvt_pk_bf16_f32 v0, v6, v44
	s_waitcnt lgkmcnt(4)
	v_cvt_pk_bf16_f32 v1, v46, v48
	s_waitcnt lgkmcnt(2)
	v_cvt_pk_bf16_f32 v2, v50, v52
	s_waitcnt lgkmcnt(0)
	v_cvt_pk_bf16_f32 v3, v54, v58
	v_lshl_add_u64 v[4:5], v[56:57], 0, v[4:5]
	global_store_dwordx4 v[4:5], v[0:3], off
	v_or_b32_e32 v4, s16, v36
	v_mul_u32_u24_e32 v4, 0xb00, v4
	v_lshlrev_b32_e32 v4, 1, v4
	v_mov_b32_e32 v5, v9
	v_cvt_pk_bf16_f32 v0, v7, v45
	v_cvt_pk_bf16_f32 v1, v47, v49
	v_cvt_pk_bf16_f32 v2, v51, v53
	v_cvt_pk_bf16_f32 v3, v55, v59
	v_lshl_add_u64 v[4:5], v[56:57], 0, v[4:5]
	global_store_dwordx4 v[4:5], v[0:3], off
	s_waitcnt lgkmcnt(0)
	s_mov_b64 s[16:17], 0

.LBB0_36:
	s_cmpk_gt_u32 s27, 0xaff
	s_cselect_b64 s[16:17], -1, 0
	s_and_b64 s[92:93], s[16:17], exec
	s_cselect_b32 s27, 0x1600000, 0
	s_add_u32 s92, s22, s27
	s_addc_u32 s93, s23, 0
	s_lshl_b32 s73, s26, 6
	v_or_b32_e32 v2, s73, v30
	v_mov_b64_e32 v[0:1], s[92:93]
	s_movk_i32 s26, 0x5800
	v_mad_u64_u32 v[0:1], s[26:27], v2, s26, v[0:1]
	v_lshl_add_u64 v[0:1], s[6:7], 2, v[0:1]
	v_lshl_add_u64 v[0:1], v[0:1], 0, v[8:9]
	s_mov_b32 s6, 0xb000
	v_add_co_u32_e32 v2, vcc, s6, v0
	s_mov_b32 s6, 0x21000
	s_nop 0
	v_addc_co_u32_e32 v3, vcc, 0, v1, vcc
	v_add_co_u32_e32 v4, vcc, s43, v0
	s_and_b64 s[26:27], s[16:17], exec
	s_nop 0
	v_addc_co_u32_e32 v5, vcc, 0, v1, vcc
	v_add_co_u32_e32 v6, vcc, s6, v0
	s_mov_b32 s6, 0x37000
	s_nop 0
	v_addc_co_u32_e32 v7, vcc, 0, v1, vcc
	v_add_co_u32_e32 v48, vcc, s45, v0
	s_nop 1
	v_addc_co_u32_e32 v49, vcc, 0, v1, vcc
	v_add_co_u32_e32 v50, vcc, s6, v0
	s_mov_b32 s6, 0x42000
	s_nop 0
	v_addc_co_u32_e32 v51, vcc, 0, v1, vcc
	v_add_co_u32_e32 v52, vcc, s6, v0
	s_mov_b32 s6, 0x4d000
	s_nop 0
	v_addc_co_u32_e32 v53, vcc, 0, v1, vcc
	v_add_co_u32_e32 v54, vcc, s6, v0
	s_mov_b32 s6, 0x58000
	s_nop 0
	v_addc_co_u32_e32 v55, vcc, 0, v1, vcc
	global_load_dword v27, v[0:1], off sc1 nt
	global_load_dword v44, v[2:3], off sc1 nt
	global_load_dword v45, v[4:5], off sc1 nt
	global_load_dword v46, v[6:7], off sc1 nt
	global_load_dword v47, v[48:49], off sc1 nt
	s_nop 0
	global_load_dword v48, v[50:51], off sc1 nt
	global_load_dword v49, v[52:53], off sc1 nt
	s_nop 0
	global_load_dword v50, v[54:55], off sc1 nt
	v_add_co_u32_e32 v2, vcc, s6, v0
	s_mov_b32 s6, 0x63000
	s_nop 0
	v_addc_co_u32_e32 v3, vcc, 0, v1, vcc
	v_add_co_u32_e32 v4, vcc, s6, v0
	s_mov_b32 s6, 0x79000
	s_nop 0
	v_addc_co_u32_e32 v5, vcc, 0, v1, vcc
	v_add_co_u32_e32 v6, vcc, s47, v0
	s_nop 1
	v_addc_co_u32_e32 v7, vcc, 0, v1, vcc
	v_add_co_u32_e32 v54, vcc, s6, v0
	s_mov_b32 s6, 0x8f000
	s_nop 0
	v_addc_co_u32_e32 v55, vcc, 0, v1, vcc
	v_add_co_u32_e32 v56, vcc, s48, v0
	s_nop 1
	v_addc_co_u32_e32 v57, vcc, 0, v1, vcc
	v_add_co_u32_e32 v58, vcc, s6, v0
	s_mov_b32 s6, 0x9a000
	s_nop 0
	v_addc_co_u32_e32 v59, vcc, 0, v1, vcc
	v_add_co_u32_e32 v60, vcc, s6, v0
	s_mov_b32 s6, 0xa5000
	s_nop 0
	v_addc_co_u32_e32 v61, vcc, 0, v1, vcc
	v_add_co_u32_e32 v62, vcc, s6, v0
	s_mov_b32 s6, 0xb0000
	s_nop 0
	v_addc_co_u32_e32 v63, vcc, 0, v1, vcc
	global_load_dword v51, v[2:3], off sc1 nt
	global_load_dword v52, v[4:5], off sc1 nt
	global_load_dword v53, v[6:7], off sc1 nt
	s_nop 0
	global_load_dword v54, v[54:55], off sc1 nt
	s_nop 0
	global_load_dword v55, v[56:57], off sc1 nt
	s_nop 0
	global_load_dword v56, v[58:59], off sc1 nt
	global_load_dword v57, v[60:61], off sc1 nt
	s_nop 0
	global_load_dword v58, v[62:63], off sc1 nt
	v_add_co_u32_e32 v2, vcc, s6, v0
	s_cselect_b32 s6, 0x1000, 0
	s_nop 0
	v_addc_co_u32_e32 v3, vcc, 0, v1, vcc
	v_add_co_u32_e32 v4, vcc, s49, v0
	s_add_u32 s26, s20, s6
	s_nop 0
	v_addc_co_u32_e32 v5, vcc, 0, v1, vcc
	v_add_co_u32_e32 v6, vcc, s50, v0
	s_addc_u32 s27, s21, 0
	s_nop 0
	v_addc_co_u32_e32 v7, vcc, 0, v1, vcc
	v_add_co_u32_e32 v62, vcc, s51, v0
	s_cmp_eq_u64 s[26:27], 0
	s_nop 0
	v_addc_co_u32_e32 v63, vcc, 0, v1, vcc
	v_add_co_u32_e32 v64, vcc, s52, v0
	s_mov_b32 s6, s73
	s_nop 0
	v_addc_co_u32_e32 v65, vcc, 0, v1, vcc
	v_add_co_u32_e32 v66, vcc, s53, v0
	s_nop 1
	v_addc_co_u32_e32 v67, vcc, 0, v1, vcc
	v_add_co_u32_e32 v68, vcc, s54, v0
	s_nop 1
	v_addc_co_u32_e32 v69, vcc, 0, v1, vcc
	v_add_co_u32_e32 v70, vcc, s55, v0
	s_nop 1
	v_addc_co_u32_e32 v71, vcc, 0, v1, vcc
	global_load_dword v59, v[2:3], off sc1 nt
	global_load_dword v60, v[4:5], off sc1 nt
	global_load_dword v61, v[6:7], off sc1 nt
	s_nop 0
	global_load_dword v62, v[62:63], off sc1 nt
	s_nop 0
	global_load_dword v63, v[64:65], off sc1 nt
	s_nop 0
	global_load_dword v64, v[66:67], off sc1 nt
	global_load_dword v65, v[68:69], off sc1 nt
	s_nop 0
	global_load_dword v66, v[70:71], off sc1 nt
	v_add_co_u32_e32 v2, vcc, s56, v0
	s_nop 1
	v_addc_co_u32_e32 v3, vcc, 0, v1, vcc
	v_add_co_u32_e32 v4, vcc, s57, v0
	s_nop 1
	v_addc_co_u32_e32 v5, vcc, 0, v1, vcc
	v_add_co_u32_e32 v6, vcc, s58, v0
	s_nop 1
	v_addc_co_u32_e32 v7, vcc, 0, v1, vcc
	v_add_co_u32_e32 v70, vcc, s59, v0
	s_nop 1
	v_addc_co_u32_e32 v71, vcc, 0, v1, vcc
	v_add_co_u32_e32 v72, vcc, s60, v0
	s_nop 1
	v_addc_co_u32_e32 v73, vcc, 0, v1, vcc
	v_add_co_u32_e32 v74, vcc, 0x13f000, v0
	s_nop 1
	v_addc_co_u32_e32 v75, vcc, 0, v1, vcc
	v_add_co_u32_e32 v76, vcc, 0x14a000, v0
	s_nop 1
	v_addc_co_u32_e32 v77, vcc, 0, v1, vcc
	v_add_co_u32_e32 v0, vcc, 0x155000, v0
	s_nop 1
	v_addc_co_u32_e32 v1, vcc, 0, v1, vcc
	global_load_dword v67, v[2:3], off sc1 nt
	global_load_dword v68, v[4:5], off sc1 nt
	global_load_dword v69, v[6:7], off sc1 nt
	s_nop 0
	global_load_dword v70, v[70:71], off sc1 nt
	s_nop 0
	global_load_dword v71, v[72:73], off sc1 nt
	s_nop 0
	global_load_dword v72, v[74:75], off sc1 nt
	global_load_dword v73, v[76:77], off sc1 nt
	s_nop 0
	global_load_dword v74, v[0:1], off sc1 nt
	s_cbranch_scc1 .LBB0_38
	s_lshl_b64 s[92:93], s[6:7], 2
	s_add_u32 s26, s26, s92
	s_addc_u32 s27, s27, s93
	v_lshlrev_b32_e32 v4, 2, v10
	global_load_dwordx4 v[0:3], v4, s[26:27] offset:16 nt
	s_nop 0
	global_load_dwordx4 v[4:7], v4, s[26:27] nt
	s_branch .LBB0_39

.LBB0_41:
	s_andn2_b64 vcc, exec, s[16:17]
	s_cbranch_vccnz .LBB0_43
	s_and_b32 s6, s40, 0x3fc0
	s_add_i32 s16, s6, 0xffffcc00
	v_or_b32_e32 v0, s16, v30
	v_mov_b32_e32 v1, v9
	s_and_b32 s26, s38, 0x3e0
	v_lshlrev_b64 v[0:1], 12, v[0:1]
	v_lshl_add_u64 v[0:1], s[18:19], 0, v[0:1]
	s_lshl_b32 s6, s26, 2
	v_lshl_add_u64 v[0:1], v[0:1], 0, s[6:7]
	v_lshl_add_u64 v[0:1], v[0:1], 0, v[8:9]
	v_add_co_u32_e32 v2, vcc, 0x2000, v0
	s_mov_b32 s17, s7
	s_nop 0
	v_addc_co_u32_e32 v3, vcc, 0, v1, vcc
	v_add_co_u32_e32 v4, vcc, 0x4000, v0
	s_nop 1
	v_addc_co_u32_e32 v5, vcc, 0, v1, vcc
	v_add_co_u32_e32 v6, vcc, 0x6000, v0
	s_nop 1
	v_addc_co_u32_e32 v7, vcc, 0, v1, vcc
	v_add_co_u32_e32 v44, vcc, 0x8000, v0
	s_nop 1
	v_addc_co_u32_e32 v45, vcc, 0, v1, vcc
	v_add_co_u32_e32 v46, vcc, 0xa000, v0
	s_nop 1
	v_addc_co_u32_e32 v47, vcc, 0, v1, vcc
	v_add_co_u32_e32 v48, vcc, 0xc000, v0
	s_nop 1
	v_addc_co_u32_e32 v49, vcc, 0, v1, vcc
	v_add_co_u32_e32 v50, vcc, 0xe000, v0
	s_nop 1
	v_addc_co_u32_e32 v51, vcc, 0, v1, vcc
	global_load_dword v27, v[0:1], off sc1 nt
	global_load_dword v54, v[2:3], off sc1 nt
	global_load_dword v55, v[4:5], off sc1 nt
	global_load_dword v56, v[6:7], off sc1 nt
	global_load_dword v57, v[44:45], off sc1 nt
	global_load_dword v58, v[46:47], off sc1 nt
	global_load_dword v59, v[48:49], off sc1 nt
	global_load_dword v60, v[50:51], off sc1 nt
	v_add_co_u32_e32 v2, vcc, 0x10000, v0
	s_nop 1
	v_addc_co_u32_e32 v3, vcc, 0, v1, vcc
	v_add_co_u32_e32 v4, vcc, 0x12000, v0
	s_nop 1
	v_addc_co_u32_e32 v5, vcc, 0, v1, vcc
	v_add_co_u32_e32 v6, vcc, 0x14000, v0
	s_nop 1
	v_addc_co_u32_e32 v7, vcc, 0, v1, vcc
	v_add_co_u32_e32 v44, vcc, 0x16000, v0
	s_nop 1
	v_addc_co_u32_e32 v45, vcc, 0, v1, vcc
	v_add_co_u32_e32 v46, vcc, 0x18000, v0
	s_nop 1
	v_addc_co_u32_e32 v47, vcc, 0, v1, vcc
	v_add_co_u32_e32 v48, vcc, 0x1a000, v0
	s_nop 1
	v_addc_co_u32_e32 v49, vcc, 0, v1, vcc
	v_add_co_u32_e32 v50, vcc, 0x1c000, v0
	s_nop 1
	v_addc_co_u32_e32 v51, vcc, 0, v1, vcc
	v_add_co_u32_e32 v52, vcc, 0x1e000, v0
	s_nop 1
	v_addc_co_u32_e32 v53, vcc, 0, v1, vcc
	global_load_dword v61, v[2:3], off sc1 nt
	global_load_dword v62, v[4:5], off sc1 nt
	global_load_dword v63, v[6:7], off sc1 nt
	global_load_dword v64, v[44:45], off sc1 nt
	global_load_dword v65, v[46:47], off sc1 nt
	global_load_dword v66, v[48:49], off sc1 nt
	global_load_dword v67, v[50:51], off sc1 nt
	global_load_dword v68, v[52:53], off sc1 nt
	v_add_co_u32_e32 v2, vcc, 0x20000, v0
	s_nop 1
	v_addc_co_u32_e32 v3, vcc, 0, v1, vcc
	v_add_co_u32_e32 v4, vcc, 0x22000, v0
	s_nop 1
	v_addc_co_u32_e32 v5, vcc, 0, v1, vcc
	v_add_co_u32_e32 v6, vcc, 0x24000, v0
	s_nop 1
	v_addc_co_u32_e32 v7, vcc, 0, v1, vcc
	v_add_co_u32_e32 v44, vcc, 0x26000, v0
	s_nop 1
	v_addc_co_u32_e32 v45, vcc, 0, v1, vcc
	v_add_co_u32_e32 v46, vcc, 0x28000, v0
	s_nop 1
	v_addc_co_u32_e32 v47, vcc, 0, v1, vcc
	v_add_co_u32_e32 v48, vcc, 0x2a000, v0
	s_nop 1
	v_addc_co_u32_e32 v49, vcc, 0, v1, vcc
	v_add_co_u32_e32 v50, vcc, 0x2c000, v0
	s_nop 1
	v_addc_co_u32_e32 v51, vcc, 0, v1, vcc
	v_add_co_u32_e32 v52, vcc, 0x2e000, v0
	s_nop 1
	v_addc_co_u32_e32 v53, vcc, 0, v1, vcc
	global_load_dword v69, v[2:3], off sc1 nt
	global_load_dword v70, v[4:5], off sc1 nt
	global_load_dword v71, v[6:7], off sc1 nt
	global_load_dword v72, v[44:45], off sc1 nt
	global_load_dword v73, v[46:47], off sc1 nt
	global_load_dword v74, v[48:49], off sc1 nt
	global_load_dword v75, v[50:51], off sc1 nt
	s_nop 0
	global_load_dword v52, v[52:53], off sc1 nt
	v_add_co_u32_e32 v2, vcc, 0x30000, v0
	s_nop 1
	v_addc_co_u32_e32 v3, vcc, 0, v1, vcc
	v_add_co_u32_e32 v4, vcc, 0x32000, v0
	s_nop 1
	v_addc_co_u32_e32 v5, vcc, 0, v1, vcc
	v_add_co_u32_e32 v6, vcc, 0x34000, v0
	s_nop 1
	v_addc_co_u32_e32 v7, vcc, 0, v1, vcc
	v_add_co_u32_e32 v44, vcc, 0x36000, v0
	s_nop 1
	v_addc_co_u32_e32 v45, vcc, 0, v1, vcc
	v_add_co_u32_e32 v46, vcc, 0x38000, v0
	s_nop 1
	v_addc_co_u32_e32 v47, vcc, 0, v1, vcc
	v_add_co_u32_e32 v48, vcc, 0x3a000, v0
	s_nop 1
	v_addc_co_u32_e32 v49, vcc, 0, v1, vcc
	v_add_co_u32_e32 v50, vcc, 0x3c000, v0
	s_nop 1
	v_addc_co_u32_e32 v51, vcc, 0, v1, vcc
	v_add_co_u32_e32 v0, vcc, 0x3e000, v0
	s_nop 1
	v_addc_co_u32_e32 v1, vcc, 0, v1, vcc
	global_load_dword v2, v[2:3], off sc1 nt
	s_nop 0
	global_load_dword v3, v[4:5], off sc1 nt
	s_nop 0
	global_load_dword v4, v[6:7], off sc1 nt
	global_load_dword v5, v[44:45], off sc1 nt
	s_nop 0
	global_load_dword v6, v[46:47], off sc1 nt
	global_load_dword v7, v[48:49], off sc1 nt
	global_load_dword v44, v[50:51], off sc1 nt
	s_nop 0
	global_load_dword v0, v[0:1], off sc1 nt
	s_waitcnt vmcnt(16)
	s_waitcnt vmcnt(0)
	ds_write2_b32 v31, v27, v54 offset1:66
	ds_write2_b32 v31, v55, v56 offset0:132 offset1:198
	ds_write2_b32 v37, v57, v58 offset0:8 offset1:74
	ds_write2_b32 v37, v59, v60 offset0:140 offset1:206
	ds_write2_b32 v38, v61, v62 offset0:16 offset1:82
	ds_write2_b32 v38, v63, v64 offset0:148 offset1:214
	ds_write2_b32 v39, v65, v66 offset0:24 offset1:90
	ds_write2_b32 v39, v67, v68 offset0:156 offset1:222
	ds_write2_b32 v40, v69, v70 offset0:32 offset1:98
	ds_write2_b32 v40, v71, v72 offset0:164 offset1:230
	ds_write2_b32 v41, v73, v74 offset0:40 offset1:106
	ds_write2_b32 v41, v75, v52 offset0:172 offset1:238
	ds_write2_b32 v42, v2, v3 offset0:48 offset1:114
	ds_write2_b32 v42, v4, v5 offset0:180 offset1:246
	ds_write2_b32 v43, v6, v7 offset0:56 offset1:122
	ds_write2_b32 v43, v44, v0 offset0:188 offset1:254
	s_waitcnt lgkmcnt(0)
	ds_read2_b32 v[4:5], v33 offset0:33 offset1:41
	ds_read2_b32 v[6:7], v33 offset1:8
	ds_read2_b32 v[44:45], v33 offset0:66 offset1:74
	ds_read2_b32 v[46:47], v33 offset0:99 offset1:107
	ds_read2_b32 v[48:49], v33 offset0:132 offset1:140
	ds_read2_b32 v[50:51], v33 offset0:165 offset1:173
	ds_read2_b32 v[52:53], v33 offset0:198 offset1:206
	ds_read2_b32 v[54:55], v33 offset0:231 offset1:239
	s_waitcnt lgkmcnt(6)
	v_cvt_pk_bf16_f32 v0, v6, v4
	v_or_b32_e32 v4, s26, v32
	v_lshl_add_u64 v[56:57], s[16:17], 1, v[12:13]
	v_lshlrev_b32_e32 v58, 11, v4
	v_mov_b32_e32 v59, v9
	s_waitcnt lgkmcnt(4)
	v_cvt_pk_bf16_f32 v1, v44, v46
	s_waitcnt lgkmcnt(2)
	v_cvt_pk_bf16_f32 v2, v48, v50
	s_waitcnt lgkmcnt(0)
	v_cvt_pk_bf16_f32 v3, v52, v54
	v_lshl_add_u64 v[58:59], v[56:57], 0, v[58:59]
	global_store_dwordx4 v[58:59], v[0:3], off
	v_or_b32_e32 v4, s26, v34
	v_lshlrev_b32_e32 v4, 11, v4
	v_cvt_pk_bf16_f32 v0, v7, v5
	v_cvt_pk_bf16_f32 v1, v45, v47
	v_cvt_pk_bf16_f32 v2, v49, v51
	v_cvt_pk_bf16_f32 v3, v53, v55
	ds_read2_b32 v[6:7], v33 offset0:49 offset1:57
	ds_read2_b32 v[44:45], v33 offset0:16 offset1:24
	ds_read2_b32 v[46:47], v33 offset0:82 offset1:90
	ds_read2_b32 v[48:49], v33 offset0:115 offset1:123
	ds_read2_b32 v[50:51], v33 offset0:148 offset1:156
	ds_read2_b32 v[52:53], v33 offset0:181 offset1:189
	ds_read2_b32 v[54:55], v33 offset0:214 offset1:222
	ds_read2_b32 v[58:59], v33 offset0:247 offset1:255
	v_mov_b32_e32 v5, v9
	v_lshl_add_u64 v[4:5], v[56:57], 0, v[4:5]
	global_store_dwordx4 v[4:5], v[0:3], off
	v_or_b32_e32 v4, s26, v35
	v_lshlrev_b32_e32 v4, 11, v4
	v_mov_b32_e32 v5, v9
	s_waitcnt lgkmcnt(6)
	v_cvt_pk_bf16_f32 v0, v44, v6
	s_waitcnt lgkmcnt(4)
	v_cvt_pk_bf16_f32 v1, v46, v48
	s_waitcnt lgkmcnt(2)
	v_cvt_pk_bf16_f32 v2, v50, v52
	s_waitcnt lgkmcnt(0)
	v_cvt_pk_bf16_f32 v3, v54, v58
	v_lshl_add_u64 v[4:5], v[56:57], 0, v[4:5]
	global_store_dwordx4 v[4:5], v[0:3], off
	v_or_b32_e32 v4, s26, v36
	v_lshlrev_b32_e32 v4, 11, v4
	v_mov_b32_e32 v5, v9
	v_cvt_pk_bf16_f32 v0, v45, v7
	v_cvt_pk_bf16_f32 v1, v47, v49
	v_cvt_pk_bf16_f32 v2, v51, v53
	v_cvt_pk_bf16_f32 v3, v55, v59
	v_lshl_add_u64 v[4:5], v[56:57], 0, v[4:5]
	global_store_dwordx4 v[4:5], v[0:3], off
	s_waitcnt lgkmcnt(0)

.LBB0_44:
	s_andn2_b64 vcc, exec, s[16:17]
	s_cbranch_vccnz .LBB0_49
	s_and_b32 s17, s40, 0x3fc0
	s_addk_i32 s17, 0xd000
	s_and_b32 s16, s38, 0x3e0
	v_or_b32_e32 v2, s17, v30
	v_mov_b64_e32 v[0:1], s[14:15]
	v_mad_u64_u32 v[0:1], s[26:27], v2, s61, v[0:1]
	s_lshl_b32 s6, s16, 2
	v_lshl_add_u64 v[0:1], v[0:1], 0, s[6:7]
	v_lshl_add_u64 v[0:1], v[0:1], 0, v[8:9]
	v_add_co_u32_e32 v2, vcc, 0x2000, v0
	s_mov_b32 s6, s17
	s_nop 0
	v_addc_co_u32_e32 v3, vcc, 0, v1, vcc
	v_add_co_u32_e32 v4, vcc, 0x8000, v0
	s_nop 1
	v_addc_co_u32_e32 v5, vcc, 0, v1, vcc
	v_add_co_u32_e32 v6, vcc, 0xe000, v0
	s_nop 1
	v_addc_co_u32_e32 v7, vcc, 0, v1, vcc
	v_add_co_u32_e32 v46, vcc, 0x14000, v0
	s_nop 1
	v_addc_co_u32_e32 v47, vcc, 0, v1, vcc
	v_add_co_u32_e32 v48, vcc, 0x1a000, v0
	s_nop 1
	v_addc_co_u32_e32 v49, vcc, 0, v1, vcc
	v_add_co_u32_e32 v50, vcc, 0x20000, v0
	s_nop 1
	v_addc_co_u32_e32 v51, vcc, 0, v1, vcc
	v_add_co_u32_e32 v52, vcc, 0x26000, v0
	s_nop 1
	v_addc_co_u32_e32 v53, vcc, 0, v1, vcc
	v_add_co_u32_e32 v54, vcc, 0x2c000, v0
	s_nop 1
	v_addc_co_u32_e32 v55, vcc, 0, v1, vcc
	global_load_dword v27, v[2:3], off sc1 nt
	global_load_dword v44, v[4:5], off offset:128 nt
	global_load_dword v45, v[6:7], off offset:256 nt
	s_nop 0
	global_load_dword v46, v[46:47], off offset:384 nt
	s_nop 0
	global_load_dword v47, v[48:49], off offset:512 nt
	s_nop 0
	global_load_dword v48, v[50:51], off offset:640 nt
	global_load_dword v49, v[52:53], off offset:768 nt
	s_nop 0
	global_load_dword v50, v[54:55], off offset:896 nt
	v_add_co_u32_e32 v2, vcc, 0x32000, v0
	s_nop 1
	v_addc_co_u32_e32 v3, vcc, 0, v1, vcc
	v_add_co_u32_e32 v4, vcc, 0x38000, v0
	s_nop 1
	v_addc_co_u32_e32 v5, vcc, 0, v1, vcc
	v_add_co_u32_e32 v6, vcc, 0x3e000, v0
	s_nop 1
	v_addc_co_u32_e32 v7, vcc, 0, v1, vcc
	v_add_co_u32_e32 v54, vcc, 0x44000, v0
	s_nop 1
	v_addc_co_u32_e32 v55, vcc, 0, v1, vcc
	v_add_co_u32_e32 v56, vcc, 0x4a000, v0
	s_nop 1
	v_addc_co_u32_e32 v57, vcc, 0, v1, vcc
	v_add_co_u32_e32 v58, vcc, 0x50000, v0
	s_nop 1
	v_addc_co_u32_e32 v59, vcc, 0, v1, vcc
	v_add_co_u32_e32 v60, vcc, 0x56000, v0
	s_nop 1
	v_addc_co_u32_e32 v61, vcc, 0, v1, vcc
	v_add_co_u32_e32 v62, vcc, 0x5c000, v0
	s_nop 1
	v_addc_co_u32_e32 v63, vcc, 0, v1, vcc
	global_load_dword v51, v[2:3], off offset:1024 nt
	global_load_dword v52, v[4:5], off offset:1152 nt
	global_load_dword v53, v[6:7], off offset:1280 nt
	s_nop 0
	global_load_dword v54, v[54:55], off offset:1408 nt
	s_nop 0
	global_load_dword v55, v[56:57], off offset:1536 nt
	s_nop 0
	global_load_dword v56, v[58:59], off offset:1664 nt
	global_load_dword v57, v[60:61], off offset:1792 nt
	s_nop 0
	global_load_dword v58, v[62:63], off offset:1920 nt
	v_add_co_u32_e32 v2, vcc, 0x62000, v0
	s_nop 1
	v_addc_co_u32_e32 v3, vcc, 0, v1, vcc
	v_add_co_u32_e32 v4, vcc, 0x68000, v0
	s_nop 1
	v_addc_co_u32_e32 v5, vcc, 0, v1, vcc
	v_add_co_u32_e32 v6, vcc, s47, v0
	s_nop 1
	v_addc_co_u32_e32 v7, vcc, 0, v1, vcc
	v_add_co_u32_e32 v62, vcc, 0x74000, v0
	s_nop 1
	v_addc_co_u32_e32 v63, vcc, 0, v1, vcc
	v_add_co_u32_e32 v64, vcc, 0x7a000, v0
	s_nop 1
	v_addc_co_u32_e32 v65, vcc, 0, v1, vcc
	v_add_co_u32_e32 v66, vcc, 0x80000, v0
	s_nop 1
	v_addc_co_u32_e32 v67, vcc, 0, v1, vcc
	v_add_co_u32_e32 v68, vcc, 0x86000, v0
	s_nop 1
	v_addc_co_u32_e32 v69, vcc, 0, v1, vcc
	v_add_co_u32_e32 v70, vcc, 0x8c000, v0
	s_nop 1
	v_addc_co_u32_e32 v71, vcc, 0, v1, vcc
	global_load_dword v59, v[2:3], off offset:2048 nt
	global_load_dword v60, v[4:5], off offset:2176 nt
	global_load_dword v61, v[6:7], off offset:2304 nt
	s_nop 0
	global_load_dword v62, v[62:63], off offset:2432 nt
	s_nop 0
	global_load_dword v63, v[64:65], off offset:2560 nt
	s_nop 0
	global_load_dword v64, v[66:67], off offset:2688 nt
	global_load_dword v65, v[68:69], off offset:2816 nt
	s_nop 0
	global_load_dword v66, v[70:71], off offset:2944 nt
	v_add_co_u32_e32 v2, vcc, 0x92000, v0
	s_nop 1
	v_addc_co_u32_e32 v3, vcc, 0, v1, vcc
	v_add_co_u32_e32 v4, vcc, 0x98000, v0
	s_nop 1
	v_addc_co_u32_e32 v5, vcc, 0, v1, vcc
	v_add_co_u32_e32 v6, vcc, 0x9e000, v0
	s_nop 1
	v_addc_co_u32_e32 v7, vcc, 0, v1, vcc
	v_add_co_u32_e32 v70, vcc, 0xa4000, v0
	s_nop 1
	v_addc_co_u32_e32 v71, vcc, 0, v1, vcc
	v_add_co_u32_e32 v72, vcc, 0xaa000, v0
	s_nop 1
	v_addc_co_u32_e32 v73, vcc, 0, v1, vcc
	v_add_co_u32_e32 v74, vcc, 0xb0000, v0
	s_nop 1
	v_addc_co_u32_e32 v75, vcc, 0, v1, vcc
	v_add_co_u32_e32 v76, vcc, 0xb6000, v0
	s_nop 1
	v_addc_co_u32_e32 v77, vcc, 0, v1, vcc
	v_add_co_u32_e32 v0, vcc, 0xbc000, v0
	s_nop 1
	v_addc_co_u32_e32 v1, vcc, 0, v1, vcc
	global_load_dword v67, v[2:3], off offset:3072 nt
	global_load_dword v68, v[4:5], off offset:3200 nt
	global_load_dword v69, v[6:7], off offset:3328 nt
	s_nop 0
	global_load_dword v70, v[70:71], off offset:3456 nt
	s_nop 0
	global_load_dword v71, v[72:73], off offset:3584 nt
	s_nop 0
	global_load_dword v72, v[74:75], off offset:3712 nt
	global_load_dword v73, v[76:77], off offset:3840 nt
	s_nop 0
	global_load_dword v74, v[0:1], off offset:3968 nt
	s_andn2_b64 vcc, exec, s[0:1]
	s_cbranch_vccnz .LBB0_47
	v_lshl_add_u64 v[4:5], s[6:7], 2, v[22:23]
	global_load_dwordx4 v[0:3], v[4:5], off offset:16 nt
	s_nop 0
	global_load_dwordx4 v[4:7], v[4:5], off nt
	s_branch .LBB0_48

.LBB0_50:
	s_andn2_b64 vcc, exec, s[16:17]
	s_cbranch_vccnz .LBB0_55
	s_and_b32 s17, s90, 0x1fc0
	s_addk_i32 s17, 0xec00
	s_and_b32 s16, s38, 0x7e0
	v_or_b32_e32 v2, s17, v30
	v_mov_b64_e32 v[0:1], s[14:15]
	v_mad_u64_u32 v[0:1], s[26:27], v2, s61, v[0:1]
	s_lshl_b32 s6, s16, 2
	v_lshl_add_u64 v[0:1], v[0:1], 0, s[6:7]
	v_lshl_add_u64 v[0:1], v[0:1], 0, v[8:9]
	v_add_co_u32_e32 v2, vcc, 0x6000, v0
	s_mov_b32 s6, s17
	s_nop 0
	v_addc_co_u32_e32 v3, vcc, 0, v1, vcc
	v_add_co_u32_e32 v4, vcc, 0xc000, v0
	s_nop 1
	v_addc_co_u32_e32 v5, vcc, 0, v1, vcc
	v_add_co_u32_e32 v6, vcc, 0x12000, v0
	s_nop 1
	v_addc_co_u32_e32 v7, vcc, 0, v1, vcc
	v_add_co_u32_e32 v48, vcc, 0x18000, v0
	s_nop 1
	v_addc_co_u32_e32 v49, vcc, 0, v1, vcc
	v_add_co_u32_e32 v50, vcc, 0x1e000, v0
	s_nop 1
	v_addc_co_u32_e32 v51, vcc, 0, v1, vcc
	v_add_co_u32_e32 v52, vcc, 0x24000, v0
	s_nop 1
	v_addc_co_u32_e32 v53, vcc, 0, v1, vcc
	v_add_co_u32_e32 v54, vcc, 0x2a000, v0
	s_nop 1
	v_addc_co_u32_e32 v55, vcc, 0, v1, vcc
	global_load_dword v27, v[0:1], off sc1 nt
	global_load_dword v44, v[2:3], off offset:128 nt
	global_load_dword v45, v[4:5], off offset:256 nt
	global_load_dword v46, v[6:7], off offset:384 nt
	global_load_dword v47, v[48:49], off offset:512 nt
	s_nop 0
	global_load_dword v48, v[50:51], off offset:640 nt
	global_load_dword v49, v[52:53], off offset:768 nt
	s_nop 0
	global_load_dword v50, v[54:55], off offset:896 nt
	v_add_co_u32_e32 v2, vcc, 0x30000, v0
	s_nop 1
	v_addc_co_u32_e32 v3, vcc, 0, v1, vcc
	v_add_co_u32_e32 v4, vcc, 0x36000, v0
	s_nop 1
	v_addc_co_u32_e32 v5, vcc, 0, v1, vcc
	v_add_co_u32_e32 v6, vcc, 0x3c000, v0
	s_nop 1
	v_addc_co_u32_e32 v7, vcc, 0, v1, vcc
	v_add_co_u32_e32 v54, vcc, 0x42000, v0
	s_nop 1
	v_addc_co_u32_e32 v55, vcc, 0, v1, vcc
	v_add_co_u32_e32 v56, vcc, 0x48000, v0
	s_nop 1
	v_addc_co_u32_e32 v57, vcc, 0, v1, vcc
	v_add_co_u32_e32 v58, vcc, 0x4e000, v0
	s_nop 1
	v_addc_co_u32_e32 v59, vcc, 0, v1, vcc
	v_add_co_u32_e32 v60, vcc, 0x54000, v0
	s_nop 1
	v_addc_co_u32_e32 v61, vcc, 0, v1, vcc
	v_add_co_u32_e32 v62, vcc, 0x5a000, v0
	s_nop 1
	v_addc_co_u32_e32 v63, vcc, 0, v1, vcc
	global_load_dword v51, v[2:3], off offset:1024 nt
	global_load_dword v52, v[4:5], off offset:1152 nt
	global_load_dword v53, v[6:7], off offset:1280 nt
	s_nop 0
	global_load_dword v54, v[54:55], off offset:1408 nt
	s_nop 0
	global_load_dword v55, v[56:57], off offset:1536 nt
	s_nop 0
	global_load_dword v56, v[58:59], off offset:1664 nt
	global_load_dword v57, v[60:61], off offset:1792 nt
	s_nop 0
	global_load_dword v58, v[62:63], off offset:1920 nt
	v_add_co_u32_e32 v2, vcc, 0x60000, v0
	s_nop 1
	v_addc_co_u32_e32 v3, vcc, 0, v1, vcc
	v_add_co_u32_e32 v4, vcc, 0x66000, v0
	s_nop 1
	v_addc_co_u32_e32 v5, vcc, 0, v1, vcc
	v_add_co_u32_e32 v6, vcc, 0x6c000, v0
	s_nop 1
	v_addc_co_u32_e32 v7, vcc, 0, v1, vcc
	v_add_co_u32_e32 v62, vcc, 0x72000, v0
	s_nop 1
	v_addc_co_u32_e32 v63, vcc, 0, v1, vcc
	v_add_co_u32_e32 v64, vcc, 0x78000, v0
	s_nop 1
	v_addc_co_u32_e32 v65, vcc, 0, v1, vcc
	v_add_co_u32_e32 v66, vcc, 0x7e000, v0
	s_nop 1
	v_addc_co_u32_e32 v67, vcc, 0, v1, vcc
	v_add_co_u32_e32 v68, vcc, s48, v0
	s_nop 1
	v_addc_co_u32_e32 v69, vcc, 0, v1, vcc
	v_add_co_u32_e32 v70, vcc, 0x8a000, v0
	s_nop 1
	v_addc_co_u32_e32 v71, vcc, 0, v1, vcc
	global_load_dword v59, v[2:3], off offset:2048 nt
	global_load_dword v60, v[4:5], off offset:2176 nt
	global_load_dword v61, v[6:7], off offset:2304 nt
	s_nop 0
	global_load_dword v62, v[62:63], off offset:2432 nt
	s_nop 0
	global_load_dword v63, v[64:65], off offset:2560 nt
	s_nop 0
	global_load_dword v64, v[66:67], off offset:2688 nt
	global_load_dword v65, v[68:69], off offset:2816 nt
	s_nop 0
	global_load_dword v66, v[70:71], off offset:2944 nt
	v_add_co_u32_e32 v2, vcc, 0x90000, v0
	s_nop 1
	v_addc_co_u32_e32 v3, vcc, 0, v1, vcc
	v_add_co_u32_e32 v4, vcc, 0x96000, v0
	s_nop 1
	v_addc_co_u32_e32 v5, vcc, 0, v1, vcc
	v_add_co_u32_e32 v6, vcc, 0x9c000, v0
	s_nop 1
	v_addc_co_u32_e32 v7, vcc, 0, v1, vcc
	v_add_co_u32_e32 v70, vcc, 0xa2000, v0
	s_nop 1
	v_addc_co_u32_e32 v71, vcc, 0, v1, vcc
	v_add_co_u32_e32 v72, vcc, 0xa8000, v0
	s_nop 1
	v_addc_co_u32_e32 v73, vcc, 0, v1, vcc
	v_add_co_u32_e32 v74, vcc, 0xae000, v0
	s_nop 1
	v_addc_co_u32_e32 v75, vcc, 0, v1, vcc
	v_add_co_u32_e32 v76, vcc, 0xb4000, v0
	s_nop 1
	v_addc_co_u32_e32 v77, vcc, 0, v1, vcc
	v_add_co_u32_e32 v0, vcc, 0xba000, v0
	s_nop 1
	v_addc_co_u32_e32 v1, vcc, 0, v1, vcc
	global_load_dword v67, v[2:3], off offset:3072 nt
	global_load_dword v68, v[4:5], off offset:3200 nt
	global_load_dword v69, v[6:7], off offset:3328 nt
	s_nop 0
	global_load_dword v70, v[70:71], off offset:3456 nt
	s_nop 0
	global_load_dword v71, v[72:73], off offset:3584 nt
	s_nop 0
	global_load_dword v72, v[74:75], off offset:3712 nt
	global_load_dword v73, v[76:77], off offset:3840 nt
	s_nop 0
	global_load_dword v74, v[0:1], off offset:3968 nt
	s_andn2_b64 vcc, exec, s[0:1]
	s_cbranch_vccnz .LBB0_53
	v_lshl_add_u64 v[4:5], s[6:7], 2, v[22:23]
	global_load_dwordx4 v[0:3], v[4:5], off offset:16 nt
	s_nop 0
	global_load_dwordx4 v[4:7], v[4:5], off nt
	s_branch .LBB0_54

.LBB0_56:
	s_andn2_b64 vcc, exec, s[16:17]
	s_cbranch_vccnz .LBB0_58
	s_and_b32 s6, s40, 0x3fc0
	s_add_i32 s16, s6, 0xffffdc00
	v_or_b32_e32 v0, s16, v30
	v_mov_b32_e32 v1, v9
	s_and_b32 s26, s38, 0x3e0
	v_lshlrev_b64 v[0:1], 12, v[0:1]
	v_lshl_add_u64 v[0:1], s[10:11], 0, v[0:1]
	s_lshl_b32 s6, s26, 2
	v_lshl_add_u64 v[0:1], v[0:1], 0, s[6:7]
	v_lshl_add_u64 v[0:1], v[0:1], 0, v[8:9]
	v_add_co_u32_e32 v2, vcc, 0x2000, v0
	s_mov_b32 s17, s7
	s_nop 0
	v_addc_co_u32_e32 v3, vcc, 0, v1, vcc
	v_add_co_u32_e32 v4, vcc, 0x4000, v0
	s_nop 1
	v_addc_co_u32_e32 v5, vcc, 0, v1, vcc
	v_add_co_u32_e32 v6, vcc, 0x6000, v0
	s_nop 1
	v_addc_co_u32_e32 v7, vcc, 0, v1, vcc
	v_add_co_u32_e32 v44, vcc, 0x8000, v0
	s_nop 1
	v_addc_co_u32_e32 v45, vcc, 0, v1, vcc
	v_add_co_u32_e32 v46, vcc, 0xa000, v0
	s_nop 1
	v_addc_co_u32_e32 v47, vcc, 0, v1, vcc
	v_add_co_u32_e32 v48, vcc, 0xc000, v0
	s_nop 1
	v_addc_co_u32_e32 v49, vcc, 0, v1, vcc
	v_add_co_u32_e32 v50, vcc, 0xe000, v0
	s_nop 1
	v_addc_co_u32_e32 v51, vcc, 0, v1, vcc
	global_load_dword v27, v[0:1], off sc1 nt
	global_load_dword v54, v[2:3], off sc1 nt
	global_load_dword v55, v[4:5], off sc1 nt
	global_load_dword v56, v[6:7], off sc1 nt
	global_load_dword v57, v[44:45], off sc1 nt
	global_load_dword v58, v[46:47], off sc1 nt
	global_load_dword v59, v[48:49], off sc1 nt
	global_load_dword v60, v[50:51], off sc1 nt
	v_add_co_u32_e32 v2, vcc, 0x10000, v0
	s_nop 1
	v_addc_co_u32_e32 v3, vcc, 0, v1, vcc
	v_add_co_u32_e32 v4, vcc, 0x12000, v0
	s_nop 1
	v_addc_co_u32_e32 v5, vcc, 0, v1, vcc
	v_add_co_u32_e32 v6, vcc, 0x14000, v0
	s_nop 1
	v_addc_co_u32_e32 v7, vcc, 0, v1, vcc
	v_add_co_u32_e32 v44, vcc, 0x16000, v0
	s_nop 1
	v_addc_co_u32_e32 v45, vcc, 0, v1, vcc
	v_add_co_u32_e32 v46, vcc, 0x18000, v0
	s_nop 1
	v_addc_co_u32_e32 v47, vcc, 0, v1, vcc
	v_add_co_u32_e32 v48, vcc, 0x1a000, v0
	s_nop 1
	v_addc_co_u32_e32 v49, vcc, 0, v1, vcc
	v_add_co_u32_e32 v50, vcc, 0x1c000, v0
	s_nop 1
	v_addc_co_u32_e32 v51, vcc, 0, v1, vcc
	v_add_co_u32_e32 v52, vcc, 0x1e000, v0
	s_nop 1
	v_addc_co_u32_e32 v53, vcc, 0, v1, vcc
	global_load_dword v61, v[2:3], off sc1 nt
	global_load_dword v62, v[4:5], off sc1 nt
	global_load_dword v63, v[6:7], off sc1 nt
	global_load_dword v64, v[44:45], off sc1 nt
	global_load_dword v65, v[46:47], off sc1 nt
	global_load_dword v66, v[48:49], off sc1 nt
	global_load_dword v67, v[50:51], off sc1 nt
	global_load_dword v68, v[52:53], off sc1 nt
	v_add_co_u32_e32 v2, vcc, 0x20000, v0
	s_nop 1
	v_addc_co_u32_e32 v3, vcc, 0, v1, vcc
	v_add_co_u32_e32 v4, vcc, 0x22000, v0
	s_nop 1
	v_addc_co_u32_e32 v5, vcc, 0, v1, vcc
	v_add_co_u32_e32 v6, vcc, 0x24000, v0
	s_nop 1
	v_addc_co_u32_e32 v7, vcc, 0, v1, vcc
	v_add_co_u32_e32 v44, vcc, 0x26000, v0
	s_nop 1
	v_addc_co_u32_e32 v45, vcc, 0, v1, vcc
	v_add_co_u32_e32 v46, vcc, 0x28000, v0
	s_nop 1
	v_addc_co_u32_e32 v47, vcc, 0, v1, vcc
	v_add_co_u32_e32 v48, vcc, 0x2a000, v0
	s_nop 1
	v_addc_co_u32_e32 v49, vcc, 0, v1, vcc
	v_add_co_u32_e32 v50, vcc, 0x2c000, v0
	s_nop 1
	v_addc_co_u32_e32 v51, vcc, 0, v1, vcc
	v_add_co_u32_e32 v52, vcc, 0x2e000, v0
	s_nop 1
	v_addc_co_u32_e32 v53, vcc, 0, v1, vcc
	global_load_dword v69, v[2:3], off sc1 nt
	global_load_dword v70, v[4:5], off sc1 nt
	global_load_dword v71, v[6:7], off sc1 nt
	global_load_dword v72, v[44:45], off sc1 nt
	global_load_dword v73, v[46:47], off sc1 nt
	global_load_dword v74, v[48:49], off sc1 nt
	global_load_dword v75, v[50:51], off sc1 nt
	s_nop 0
	global_load_dword v52, v[52:53], off sc1 nt
	v_add_co_u32_e32 v2, vcc, 0x30000, v0
	s_nop 1
	v_addc_co_u32_e32 v3, vcc, 0, v1, vcc
	v_add_co_u32_e32 v4, vcc, 0x32000, v0
	s_nop 1
	v_addc_co_u32_e32 v5, vcc, 0, v1, vcc
	v_add_co_u32_e32 v6, vcc, 0x34000, v0
	s_nop 1
	v_addc_co_u32_e32 v7, vcc, 0, v1, vcc
	v_add_co_u32_e32 v44, vcc, 0x36000, v0
	s_nop 1
	v_addc_co_u32_e32 v45, vcc, 0, v1, vcc
	v_add_co_u32_e32 v46, vcc, 0x38000, v0
	s_nop 1
	v_addc_co_u32_e32 v47, vcc, 0, v1, vcc
	v_add_co_u32_e32 v48, vcc, 0x3a000, v0
	s_nop 1
	v_addc_co_u32_e32 v49, vcc, 0, v1, vcc
	v_add_co_u32_e32 v50, vcc, 0x3c000, v0
	s_nop 1
	v_addc_co_u32_e32 v51, vcc, 0, v1, vcc
	v_add_co_u32_e32 v0, vcc, 0x3e000, v0
	s_nop 1
	v_addc_co_u32_e32 v1, vcc, 0, v1, vcc
	global_load_dword v2, v[2:3], off sc1 nt
	s_nop 0
	global_load_dword v3, v[4:5], off sc1 nt
	s_nop 0
	global_load_dword v4, v[6:7], off sc1 nt
	global_load_dword v5, v[44:45], off sc1 nt
	s_nop 0
	global_load_dword v6, v[46:47], off sc1 nt
	global_load_dword v7, v[48:49], off sc1 nt
	global_load_dword v44, v[50:51], off sc1 nt
	s_nop 0
	global_load_dword v0, v[0:1], off sc1 nt
	s_waitcnt vmcnt(16)
	s_waitcnt vmcnt(0)
	ds_write2_b32 v31, v27, v54 offset1:66
	ds_write2_b32 v31, v55, v56 offset0:132 offset1:198
	ds_write2_b32 v37, v57, v58 offset0:8 offset1:74
	ds_write2_b32 v37, v59, v60 offset0:140 offset1:206
	ds_write2_b32 v38, v61, v62 offset0:16 offset1:82
	ds_write2_b32 v38, v63, v64 offset0:148 offset1:214
	ds_write2_b32 v39, v65, v66 offset0:24 offset1:90
	ds_write2_b32 v39, v67, v68 offset0:156 offset1:222
	ds_write2_b32 v40, v69, v70 offset0:32 offset1:98
	ds_write2_b32 v40, v71, v72 offset0:164 offset1:230
	ds_write2_b32 v41, v73, v74 offset0:40 offset1:106
	ds_write2_b32 v41, v75, v52 offset0:172 offset1:238
	ds_write2_b32 v42, v2, v3 offset0:48 offset1:114
	ds_write2_b32 v42, v4, v5 offset0:180 offset1:246
	ds_write2_b32 v43, v6, v7 offset0:56 offset1:122
	ds_write2_b32 v43, v44, v0 offset0:188 offset1:254
	s_waitcnt lgkmcnt(0)
	ds_read2_b32 v[4:5], v33 offset0:33 offset1:41
	ds_read2_b32 v[6:7], v33 offset1:8
	ds_read2_b32 v[44:45], v33 offset0:66 offset1:74
	ds_read2_b32 v[46:47], v33 offset0:99 offset1:107
	ds_read2_b32 v[48:49], v33 offset0:132 offset1:140
	ds_read2_b32 v[50:51], v33 offset0:165 offset1:173
	ds_read2_b32 v[52:53], v33 offset0:198 offset1:206
	ds_read2_b32 v[54:55], v33 offset0:231 offset1:239
	s_waitcnt lgkmcnt(6)
	v_cvt_pk_bf16_f32 v0, v6, v4
	v_or_b32_e32 v4, s26, v32
	v_lshl_add_u64 v[56:57], s[16:17], 1, v[14:15]
	v_lshlrev_b32_e32 v58, 11, v4
	v_mov_b32_e32 v59, v9
	s_waitcnt lgkmcnt(4)
	v_cvt_pk_bf16_f32 v1, v44, v46
	s_waitcnt lgkmcnt(2)
	v_cvt_pk_bf16_f32 v2, v48, v50
	s_waitcnt lgkmcnt(0)
	v_cvt_pk_bf16_f32 v3, v52, v54
	v_lshl_add_u64 v[58:59], v[56:57], 0, v[58:59]
	global_store_dwordx4 v[58:59], v[0:3], off
	v_or_b32_e32 v4, s26, v34
	v_lshlrev_b32_e32 v4, 11, v4
	v_cvt_pk_bf16_f32 v0, v7, v5
	v_cvt_pk_bf16_f32 v1, v45, v47
	v_cvt_pk_bf16_f32 v2, v49, v51
	v_cvt_pk_bf16_f32 v3, v53, v55
	ds_read2_b32 v[6:7], v33 offset0:49 offset1:57
	ds_read2_b32 v[44:45], v33 offset0:16 offset1:24
	ds_read2_b32 v[46:47], v33 offset0:82 offset1:90
	ds_read2_b32 v[48:49], v33 offset0:115 offset1:123
	ds_read2_b32 v[50:51], v33 offset0:148 offset1:156
	ds_read2_b32 v[52:53], v33 offset0:181 offset1:189
	ds_read2_b32 v[54:55], v33 offset0:214 offset1:222
	ds_read2_b32 v[58:59], v33 offset0:247 offset1:255
	v_mov_b32_e32 v5, v9
	v_lshl_add_u64 v[4:5], v[56:57], 0, v[4:5]
	global_store_dwordx4 v[4:5], v[0:3], off
	v_or_b32_e32 v4, s26, v35
	v_lshlrev_b32_e32 v4, 11, v4
	v_mov_b32_e32 v5, v9
	s_waitcnt lgkmcnt(6)
	v_cvt_pk_bf16_f32 v0, v44, v6
	s_waitcnt lgkmcnt(4)
	v_cvt_pk_bf16_f32 v1, v46, v48
	s_waitcnt lgkmcnt(2)
	v_cvt_pk_bf16_f32 v2, v50, v52
	s_waitcnt lgkmcnt(0)
	v_cvt_pk_bf16_f32 v3, v54, v58
	v_lshl_add_u64 v[4:5], v[56:57], 0, v[4:5]
	global_store_dwordx4 v[4:5], v[0:3], off
	v_or_b32_e32 v4, s26, v36
	v_lshlrev_b32_e32 v4, 11, v4
	v_mov_b32_e32 v5, v9
	v_cvt_pk_bf16_f32 v0, v45, v7
	v_cvt_pk_bf16_f32 v1, v47, v49
	v_cvt_pk_bf16_f32 v2, v51, v53
	v_cvt_pk_bf16_f32 v3, v55, v59
	v_lshl_add_u64 v[4:5], v[56:57], 0, v[4:5]
	global_store_dwordx4 v[4:5], v[0:3], off
	s_waitcnt lgkmcnt(0)

.LBB0_59:
	s_andn2_b64 vcc, exec, s[16:17]
	s_cbranch_vccnz .LBB0_23
	s_mul_hi_i32 s6, s90, 0x38e38e39
	s_lshr_b32 s16, s6, 31
	s_ashr_i32 s6, s6, 6
	s_add_i32 s6, s6, s16
	s_lshl_b32 s26, s6, 6
	s_mulk_i32 s6, 0xdc00
	s_add_i32 s16, s38, s6
	v_or_b32_e32 v2, s26, v30
	v_mov_b64_e32 v[0:1], s[8:9]
	v_mad_i64_i32 v[0:1], s[72:73], v2, s69, v[0:1]
	s_ashr_i32 s17, s16, 31
	v_lshl_add_u64 v[0:1], s[16:17], 2, v[0:1]
	v_lshl_add_u64 v[0:1], v[0:1], 0, v[8:9]
	v_add_co_u32_e32 v2, vcc, s42, v0
	s_ashr_i32 s27, s26, 31
	s_nop 0
	v_addc_co_u32_e32 v3, vcc, 0, v1, vcc
	v_add_co_u32_e32 v4, vcc, s44, v0
	s_nop 1
	v_addc_co_u32_e32 v5, vcc, 0, v1, vcc
	v_add_co_u32_e32 v6, vcc, s46, v0
	s_nop 1
	v_addc_co_u32_e32 v7, vcc, 0, v1, vcc
	v_add_co_u32_e32 v48, vcc, s62, v0
	s_nop 1
	v_addc_co_u32_e32 v49, vcc, 0, v1, vcc
	v_add_co_u32_e32 v50, vcc, s63, v0
	s_nop 1
	v_addc_co_u32_e32 v51, vcc, 0, v1, vcc
	v_add_co_u32_e32 v52, vcc, s64, v0
	s_nop 1
	v_addc_co_u32_e32 v53, vcc, 0, v1, vcc
	v_add_co_u32_e32 v54, vcc, s65, v0
	s_nop 1
	v_addc_co_u32_e32 v55, vcc, 0, v1, vcc
	global_load_dword v27, v[0:1], off sc1 nt
	global_load_dword v44, v[2:3], off sc1 nt
	global_load_dword v45, v[4:5], off sc1 nt
	global_load_dword v46, v[6:7], off sc1 nt
	global_load_dword v47, v[48:49], off sc1 nt
	s_nop 0
	global_load_dword v48, v[50:51], off sc1 nt
	global_load_dword v49, v[52:53], off sc1 nt
	s_nop 0
	global_load_dword v50, v[54:55], off sc1 nt
	v_add_co_u32_e32 v2, vcc, s66, v0
	s_nop 1
	v_addc_co_u32_e32 v3, vcc, 0, v1, vcc
	v_add_co_u32_e32 v4, vcc, s67, v0
	s_nop 1
	v_addc_co_u32_e32 v5, vcc, 0, v1, vcc
	v_add_co_u32_e32 v6, vcc, s68, v0
	s_nop 1
	v_addc_co_u32_e32 v7, vcc, 0, v1, vcc
	v_add_co_u32_e32 v54, vcc, s50, v0
	s_nop 1
	v_addc_co_u32_e32 v55, vcc, 0, v1, vcc
	v_add_co_u32_e32 v56, vcc, s70, v0
	s_nop 1
	v_addc_co_u32_e32 v57, vcc, 0, v1, vcc
	v_add_co_u32_e32 v58, vcc, s71, v0
	s_nop 1
	v_addc_co_u32_e32 v59, vcc, 0, v1, vcc
	v_add_co_u32_e32 v60, vcc, s74, v0
	s_nop 1
	v_addc_co_u32_e32 v61, vcc, 0, v1, vcc
	v_add_co_u32_e32 v62, vcc, s75, v0
	s_nop 1
	v_addc_co_u32_e32 v63, vcc, 0, v1, vcc
	global_load_dword v51, v[2:3], off sc1 nt
	global_load_dword v52, v[4:5], off sc1 nt
	global_load_dword v53, v[6:7], off sc1 nt
	s_nop 0
	global_load_dword v54, v[54:55], off sc1 nt
	s_nop 0
	global_load_dword v55, v[56:57], off sc1 nt
	s_nop 0
	global_load_dword v56, v[58:59], off sc1 nt
	global_load_dword v57, v[60:61], off sc1 nt
	s_nop 0
	global_load_dword v58, v[62:63], off sc1 nt
	v_add_co_u32_e32 v2, vcc, s76, v0
	s_nop 1
	v_addc_co_u32_e32 v3, vcc, 0, v1, vcc
	v_add_co_u32_e32 v4, vcc, s77, v0
	s_nop 1
	v_addc_co_u32_e32 v5, vcc, 0, v1, vcc
	v_add_co_u32_e32 v6, vcc, s78, v0
	s_nop 1
	v_addc_co_u32_e32 v7, vcc, 0, v1, vcc
	v_add_co_u32_e32 v62, vcc, s79, v0
	s_nop 1
	v_addc_co_u32_e32 v63, vcc, 0, v1, vcc
	v_add_co_u32_e32 v64, vcc, s80, v0
	s_nop 1
	v_addc_co_u32_e32 v65, vcc, 0, v1, vcc
	v_add_co_u32_e32 v66, vcc, s81, v0
	s_nop 1
	v_addc_co_u32_e32 v67, vcc, 0, v1, vcc
	v_add_co_u32_e32 v68, vcc, s82, v0
	s_nop 1
	v_addc_co_u32_e32 v69, vcc, 0, v1, vcc
	v_add_co_u32_e32 v70, vcc, s83, v0
	s_nop 1
	v_addc_co_u32_e32 v71, vcc, 0, v1, vcc
	global_load_dword v59, v[2:3], off sc1 nt
	global_load_dword v60, v[4:5], off sc1 nt
	global_load_dword v61, v[6:7], off sc1 nt
	s_nop 0
	global_load_dword v62, v[62:63], off sc1 nt
	s_nop 0
	global_load_dword v63, v[64:65], off sc1 nt
	s_nop 0
	global_load_dword v64, v[66:67], off sc1 nt
	global_load_dword v65, v[68:69], off sc1 nt
	s_nop 0
	global_load_dword v66, v[70:71], off sc1 nt
	v_add_co_u32_e32 v2, vcc, s84, v0
	s_nop 1
	v_addc_co_u32_e32 v3, vcc, 0, v1, vcc
	v_add_co_u32_e32 v4, vcc, s85, v0
	s_nop 1
	v_addc_co_u32_e32 v5, vcc, 0, v1, vcc
	v_add_co_u32_e32 v6, vcc, s86, v0
	s_nop 1
	v_addc_co_u32_e32 v7, vcc, 0, v1, vcc
	v_add_co_u32_e32 v70, vcc, s87, v0
	s_nop 1
	v_addc_co_u32_e32 v71, vcc, 0, v1, vcc
	v_add_co_u32_e32 v72, vcc, s88, v0
	s_nop 1
	v_addc_co_u32_e32 v73, vcc, 0, v1, vcc
	v_add_co_u32_e32 v74, vcc, s89, v0
	s_nop 1
	v_addc_co_u32_e32 v75, vcc, 0, v1, vcc
	v_add_co_u32_e32 v76, vcc, 0x21c000, v0
	s_nop 1
	v_addc_co_u32_e32 v77, vcc, 0, v1, vcc
	v_add_co_u32_e32 v0, vcc, 0x22e000, v0
	s_nop 1
	v_addc_co_u32_e32 v1, vcc, 0, v1, vcc
	global_load_dword v67, v[2:3], off sc1 nt
	global_load_dword v68, v[4:5], off sc1 nt
	global_load_dword v69, v[6:7], off sc1 nt
	s_nop 0
	global_load_dword v70, v[70:71], off sc1 nt
	s_nop 0
	global_load_dword v71, v[72:73], off sc1 nt
	s_nop 0
	global_load_dword v72, v[74:75], off sc1 nt
	global_load_dword v73, v[76:77], off sc1 nt
	s_nop 0
	global_load_dword v74, v[0:1], off sc1 nt
	s_andn2_b64 vcc, exec, s[2:3]
	s_cbranch_vccz .LBB0_21
	v_mov_b32_e32 v0, 1.0
	v_mov_b32_e32 v1, v0
	v_mov_b32_e32 v2, v0
	v_mov_b32_e32 v3, v0
	v_mov_b32_e32 v4, v0
	v_mov_b32_e32 v5, v0
	v_mov_b32_e32 v6, v0
	v_mov_b32_e32 v7, v0
	s_branch .LBB0_22

.LBB0_66:
	v_ashrrev_i32_e32 v14, 10, v6
	v_and_b32_e32 v2, 0x3ff, v6
	v_ashrrev_i32_e32 v15, 31, v14
	v_mad_u64_u32 v[18:19], s[26:27], v2, s21, v[0:1]
	v_ashrrev_i32_e32 v16, 10, v7
	v_and_b32_e32 v5, 0x3ff, v7
	v_lshl_add_u64 v[18:19], v[14:15], 2, v[18:19]
	v_ashrrev_i32_e32 v17, 31, v16
	v_mad_u64_u32 v[20:21], s[26:27], v5, s21, v[0:1]
	v_add_co_u32_e32 v18, vcc, s22, v18
	v_lshl_add_u64 v[20:21], v[16:17], 2, v[20:21]
	s_nop 0
	v_addc_co_u32_e32 v19, vcc, 0, v19, vcc
	v_lshlrev_b32_e32 v13, 2, v2
	v_lshlrev_b32_e32 v24, 2, v5
	v_add_co_u32_e32 v20, vcc, s22, v20
	global_load_dword v22, v13, s[12:13] nt
	global_load_dword v23, v24, s[12:13] nt
	v_addc_co_u32_e32 v21, vcc, 0, v21, vcc
	global_load_dword v24, v[18:19], off sc1 nt
	global_load_dword v25, v[20:21], off sc1 nt
	v_lshlrev_b64 v[14:15], 11, v[14:15]
	v_add_u32_e32 v12, -2, v12
	v_lshlrev_b32_e32 v2, 1, v2
	v_lshl_add_u64 v[14:15], s[8:9], 0, v[14:15]
	v_cmp_eq_u32_e32 vcc, 0, v12
	v_lshlrev_b64 v[16:17], 11, v[16:17]
	v_lshl_add_u64 v[14:15], v[14:15], 0, v[2:3]
	s_or_b64 s[18:19], vcc, s[18:19]
	v_lshl_add_u64 v[16:17], s[8:9], 0, v[16:17]
	v_lshlrev_b32_e32 v2, 1, v5
	v_add_co_u32_e32 v14, vcc, s24, v14
	v_lshl_add_u64 v[16:17], v[16:17], 0, v[2:3]
	s_nop 0
	v_addc_co_u32_e32 v15, vcc, 0, v15, vcc
	v_add_u32_e32 v7, s20, v7
	v_add_u32_e32 v6, s1, v6
	v_add_co_u32_e32 v16, vcc, 0x400000, v16
	s_waitcnt vmcnt(0)
	v_pk_mul_f32 v[18:19], v[24:25], v[22:23]
	s_nop 0
	v_and_b32_sdwa v5, v18, v10 dst_sel:DWORD dst_unused:UNUSED_PAD src0_sel:WORD_1 src1_sel:DWORD
	v_and_b32_sdwa v2, v19, v10 dst_sel:DWORD dst_unused:UNUSED_PAD src0_sel:WORD_1 src1_sel:DWORD
	v_add3_u32 v5, v18, v5, s23
	v_addc_co_u32_e32 v17, vcc, 0, v17, vcc
	v_add3_u32 v2, v19, v2, s23
	global_store_short_d16_hi v[14:15], v5, off
	global_store_short_d16_hi v[16:17], v2, off
	s_andn2_b64 exec, exec, s[18:19]
	s_cbranch_execnz .LBB0_66
	s_or_b64 exec, exec, s[18:19]
	v_mad_u64_u32 v[0:1], s[18:19], v9, s0, v[4:5]
	v_cmp_ne_u32_e32 vcc, v8, v9
	s_orn2_b64 s[18:19], vcc, exec

.LBB0_71:
	v_ashrrev_i32_e32 v8, 10, v0
	v_and_b32_e32 v1, 0x3ff, v0
	v_ashrrev_i32_e32 v9, 31, v8
	v_mad_u64_u32 v[12:13], s[14:15], v1, s1, v[2:3]
	v_lshl_add_u64 v[12:13], v[8:9], 2, v[12:13]
	v_add_co_u32_e32 v12, vcc, 0x3000, v12
	v_lshlrev_b32_e32 v5, 2, v1
	s_nop 0
	v_addc_co_u32_e32 v13, vcc, 0, v13, vcc
	global_load_dword v5, v5, s[12:13] nt
	v_lshlrev_b64 v[8:9], 11, v[8:9]
	global_load_dword v10, v[12:13], off sc1 nt
	v_add_u32_e32 v0, s0, v0
	v_lshlrev_b32_e32 v6, 1, v1
	v_lshl_add_u64 v[8:9], s[8:9], 0, v[8:9]
	v_cmp_lt_i32_e32 vcc, s11, v0
	v_lshl_add_u64 v[8:9], v[8:9], 0, v[6:7]
	s_or_b64 s[2:3], vcc, s[2:3]
	v_add_co_u32_e32 v8, vcc, 0x400000, v8
	s_waitcnt vmcnt(0)
	v_mul_f32_e32 v1, v10, v5
	v_bfe_u32 v5, v1, 16, 1
	v_addc_co_u32_e32 v9, vcc, 0, v9, vcc
	v_add3_u32 v1, v1, v5, s10
	global_store_short_d16_hi v[8:9], v1, off
	s_andn2_b64 exec, exec, s[2:3]
	s_cbranch_execnz .LBB0_71
